# attention: no static priority raise for group 1
# baseline (speedup 1.0000x reference)
; __device__ __forceinline__ void attn_unit_pp(int b, int h, int qb, int par, const bf16_t* __restrict__ QBp, const bf16_t* __restrict__ KBp, const bf16_t* __restrict__ VBp, ...
;     ...
;   __syncthreads();
;   if (g == 1) { __builtin_amdgcn_s_setprio(1); __syncthreads(); }
.LBB0_360:
	s_cmp_lg_u32 s38, 1
	s_cselect_b64 s[0:1], -1, 0
	s_and_b64 vcc, exec, s[0:1]
	s_waitcnt lgkmcnt(0)
	s_barrier
	s_cbranch_vccnz .LBB0_362
	s_nop 0
	s_barrier
